# ssd_prompt: dt scan for all 16 chunks precomputed by all waves before the chunk loop (per-chunk LDS area), in-loop scan removed; LDS-read hoisting also in the yi/epilogue and state-update sections
# baseline (speedup 1.0000x reference)
.LBB0_383:
	v_writelane_b32 v236, s82, 0
	s_nop 1
	v_writelane_b32 v236, s83, 1
	v_writelane_b32 v236, s90, 2
	s_nop 1
	v_writelane_b32 v236, s91, 3
	s_or_b64 exec, exec, s[0:1]
	s_add_u32 s0, s92, 0xed00000
	s_addc_u32 s1, s93, 0
	v_writelane_b32 v236, s0, 4
	s_movk_i32 s73, 0x1000
	s_waitcnt lgkmcnt(0)
	v_mbcnt_lo_u32_b32 v0, -1, 0
	v_writelane_b32 v236, s1, 5
	s_bfe_u32 s0, s76, 0x10003
	s_cmpk_lt_i32 s20, 0x1000
	v_writelane_b32 v236, s0, 6
	s_cselect_b64 s[0:1], -1, 0
	v_writelane_b32 v236, s0, 7
	s_mov_b32 s43, 0
	s_movk_i32 s91, 0x3000
	v_writelane_b32 v236, s1, 8
	s_lshl_b32 s0, s33, 12
	s_add_i32 s87, s0, 0
	s_add_u32 s0, s92, 0x1b800000
	v_writelane_b32 v236, s0, 9
	s_addc_u32 s0, s93, 0
	v_writelane_b32 v236, s0, 11
	s_add_u32 s0, s92, 0xeb00000
	s_addc_u32 s1, s93, 0
	v_writelane_b32 v236, s0, 12
	s_movk_i32 s90, 0x6000
	s_mov_b32 s77, 0x3f2aaaab
	v_writelane_b32 v236, s1, 13
	v_readlane_b32 s0, v237, 0
	v_readlane_b32 s6, v237, 6
	v_readlane_b32 s7, v237, 7
	s_add_u32 s0, s6, 0x6aa4000
	v_writelane_b32 v236, s0, 14
	s_addc_u32 s0, s7, 0
	v_writelane_b32 v236, s0, 15
	s_add_u32 s0, s92, 0x8000
	v_writelane_b32 v236, s0, 16
	s_addc_u32 s0, s93, 0
	v_readlane_b32 s1, v237, 1
	s_cmpk_lt_i32 s76, 0x100
	v_writelane_b32 v236, s0, 17
	s_cselect_b64 s[0:1], -1, 0
	v_writelane_b32 v236, s0, 18
	v_readlane_b32 s2, v237, 2
	v_readlane_b32 s3, v237, 3
	v_writelane_b32 v236, s1, 19
	s_add_u32 s0, s6, 0x4200000
	s_addc_u32 s1, s7, 0
	v_writelane_b32 v236, s0, 20
	v_readlane_b32 s4, v237, 4
	v_readlane_b32 s5, v237, 5
	v_writelane_b32 v236, s1, 21
	s_add_u32 s0, s6, 0x5200000
	s_addc_u32 s1, s7, 0
	v_writelane_b32 v236, s0, 22
	s_mov_b64 s[4:5], -1
	v_mov_b32_e32 v110, 0x3ecc95a3
	v_writelane_b32 v236, s1, 23
	s_add_u32 s0, s92, 0x1b801000
	v_writelane_b32 v236, s0, 24
	s_addc_u32 s0, s93, 0
	v_writelane_b32 v236, s0, 25
	s_add_u32 s0, s6, 0x66a4000
	v_writelane_b32 v236, s0, 26
	s_addc_u32 s0, s7, 0
	v_writelane_b32 v236, s0, 27
	s_add_u32 s0, s6, 0x4100000
	s_addc_u32 s1, s7, 0
	v_writelane_b32 v236, s0, 28
	s_mov_b32 s33, 0x3f317218
	s_mov_b32 s80, 0x7f800000
	v_writelane_b32 v236, s1, 29
	s_add_u32 s0, s6, 0x4180000
	s_addc_u32 s1, s7, 0
	v_writelane_b32 v236, s0, 30
	s_mov_b32 s81, 0x33800000
	v_mov_b32_e32 v2, 0
	v_writelane_b32 v236, s1, 31
	s_lshl_b32 s0, s76, 1
	v_writelane_b32 v236, s0, 32
	s_lshl_b32 s0, s96, 1
	v_writelane_b32 v236, s0, 33
	v_writelane_b32 v236, s76, 34
	s_lshl_b32 s0, s76, 5
	v_writelane_b32 v236, s0, 35
	v_writelane_b32 v237, s96, 60
	s_lshl_b32 s0, s96, 5
	v_writelane_b32 v236, s0, 36
	v_writelane_b32 v237, s97, 61
	s_mov_b32 s76, 0x41a00000
	s_movk_i32 s38, 0x1800
	s_mov_b32 s39, 0x800000
	v_mov_b32_e32 v111, 0x358637bd
	s_add_i32 s59, 0, 0x16000
	s_movk_i32 s97, 0x50
	s_add_i32 s78, 0, 0x11000
	s_add_i32 s79, 0, 0x19000
	s_add_i32 s89, 0, 0x19200
	s_add_i32 s96, 0, 0x19400
	s_movk_i32 s68, 0x60
	s_mov_b32 s69, 0x5040100
	s_movk_i32 s86, 0x41
	s_movk_i32 s88, 0x42
	s_movk_i32 s52, 0x4f
	s_movk_i32 s53, 0x51
	s_movk_i32 s54, 0x52
	s_movk_i32 s55, 0x5f
	s_movk_i32 s56, 0x61
	s_movk_i32 s57, 0x62
	s_add_i32 s58, 0, 0x185fc
	s_movk_i32 s82, 0x90
	v_mov_b32_e32 v74, 0x3f317218
	v_mov_b32_e32 v112, 0x7f800000
	v_mov_b32_e32 v113, 0x7fc00000
	v_mov_b32_e32 v114, 0xff800000
	v_mbcnt_hi_u32_b32 v73, -1, v0
	v_mov_b32_e32 v115, 0x3600
	v_mov_b32_e32 v116, 0xc00000
	v_bfrev_b32_e32 v117, 0.5
	v_mov_b32_e32 v118, 0xf149f2ca
	s_mov_b32 s0, 0
	s_mov_b64 s[70:71], 0xc0000
	s_barrier
	s_branch .LBB0_385

.LBB0_464:
	s_lshl_b32 s2, s60, 1
	s_and_b32 s30, s7, 31
	s_and_b32 s66, s2, 64
	s_lshl_b32 s2, s7, 5
	s_lshl_b32 s40, s64, 4
	s_lshl_b32 s65, s30, 7
	s_and_b32 s67, s2, 0x300
	s_ashr_i32 s41, s40, 31
	s_waitcnt vmcnt(11)
	v_mul_f32_e32 v9, 0x3fb8aa3b, v9
	s_add_u32 s2, s4, s40
	v_exp_f32_e32 v119, v9
	v_or_b32_e32 v9, s2, v70
	v_mov_b64_e32 v[48:49], s[74:75]
	s_movk_i32 s16, 0x3600
	s_addc_u32 s4, s5, s41
	v_mad_u64_u32 v[48:49], s[2:3], v9, s16, v[48:49]
	v_mad_i32_i24 v49, s4, v115, v49
	s_lshl_b32 s2, s8, 1
	s_mov_b32 s3, s43
	v_lshrrev_b32_e32 v47, 4, v11
	v_lshl_add_u64 v[48:49], v[48:49], 0, s[2:3]
	v_lshl_add_u64 v[48:49], v[48:49], 0, s[42:43]
	v_lshlrev_b32_e32 v50, 3, v47
	v_mov_b32_e32 v51, v2
	v_lshl_add_u64 v[48:49], v[48:49], 0, v[50:51]
	global_load_dwordx2 v[98:99], v[48:49], off offset:3072
	global_load_dwordx2 v[96:97], v[48:49], off offset:3104
	v_mul_lo_u32 v9, v0, s97
	v_add3_u32 v121, s78, v9, v46
	v_lshlrev_b32_e32 v46, 2, v11
	v_or_b32_e32 v48, 0x100, v46
	v_and_b32_e32 v49, 48, v11
	v_add_u32_e32 v122, s79, v48
	v_add_u32_e32 v123, s89, v48
	v_add_u32_e32 v124, s96, v48
	v_add_u32_e32 v125, s79, v46
	v_add_u32_e32 v126, s89, v46
	v_add_u32_e32 v127, s96, v46
	v_or_b32_e32 v46, s40, v70
	v_add_u32_e32 v48, 0, v49
	s_movk_i32 s14, 0x110
	v_mad_u64_u32 v[78:79], s[2:3], v46, s14, v[48:49]
	v_mad_u32_u24 v79, v70, s14, v48
	v_or_b32_e32 v48, 64, v49
	v_add_u32_e32 v133, s89, v48
	v_add_u32_e32 v134, s79, v48
	v_or_b32_e32 v48, 0x80, v49
	v_add_u32_e32 v135, s89, v48
	v_add_u32_e32 v136, s79, v48
	v_or_b32_e32 v48, 0xc0, v49
	s_cmp_gt_u32 s6, 63
	v_add_u32_e32 v137, s89, v48
	v_add_u32_e32 v138, s79, v48
	v_or_b32_e32 v48, 0x100, v49
	s_cselect_b64 s[72:73], -1, 0
	v_add_u32_e32 v139, s89, v48
	v_add_u32_e32 v140, s79, v48
	v_or_b32_e32 v48, 0x140, v49
	s_lshl_b32 s4, s64, 5
	v_lshlrev_b32_e32 v45, 3, v70
	v_add_u32_e32 v141, s89, v48
	v_add_u32_e32 v142, s79, v48
	v_or_b32_e32 v48, 0x180, v49
	s_add_i32 s5, s4, 0
	v_lshlrev_b32_e32 v9, 1, v45
	v_add_u32_e32 v143, s89, v48
	v_add_u32_e32 v144, s79, v48
	v_lshrrev_b32_e32 v48, 2, v70
	v_add_u32_e32 v52, s5, v1
	v_add_u32_e32 v53, s78, v1
	v_mul_lo_u32 v1, v10, s14
	v_add3_u32 v150, 0, v9, v1
	v_or_b32_e32 v1, v50, v48
	v_lshlrev_b32_e32 v76, 2, v47
	v_and_b32_e32 v45, 24, v45
	v_mul_u32_u24_e32 v9, 0x110, v1
	v_mul_u32_u24_e32 v55, 0x50, v1
	v_or_b32_e32 v1, 32, v50
	v_add_u32_e32 v145, s78, v45
	v_or_b32_e32 v45, v76, v48
	v_lshl_add_u32 v152, v47, 5, s96
	v_or_b32_e32 v47, v1, v48
	v_lshl_add_u32 v153, v1, 2, s96
	v_or_b32_e32 v1, 64, v50
	s_lshl_b64 s[14:15], s[0:1], 18
	v_mul_u32_u24_e32 v146, 0x50, v45
	v_mad_u32_u24 v147, v45, s97, v145
	v_or_b32_e32 v45, 0x1c0, v49
	s_mov_b32 s6, s59
	v_mul_u32_u24_e32 v56, 0x110, v47
	v_mul_u32_u24_e32 v57, 0x50, v47
	v_or_b32_e32 v47, v1, v48
	v_lshl_add_u32 v154, v1, 2, s96
	v_or_b32_e32 v1, 0x60, v50
	v_mov_b32_e32 v81, s15
	s_mul_i32 s15, s0, 0x1b00000
	v_add_u32_e32 v131, s89, v49
	v_add_u32_e32 v132, s79, v49
	v_add_u32_e32 v148, s89, v45
	v_add_u32_e32 v149, s79, v45
	v_add_u32_e32 v45, s6, v49
	v_mul_lo_u32 v49, v46, s97
	v_mul_u32_u24_e32 v58, 0x110, v47
	v_mul_u32_u24_e32 v59, 0x50, v47
	v_or_b32_e32 v47, v1, v48
	v_lshl_add_u32 v155, v1, 2, s96
	v_lshl_or_b32 v1, v11, 7, s14
	s_mul_hi_i32 s14, s0, 0x1b00000
	s_or_b32 s15, s15, s65
	v_add3_u32 v151, s78, v49, v50
	v_mov_b32_e32 v48, s15
	v_mov_b32_e32 v49, s14
	s_add_i32 s4, s59, s4
	v_mad_i64_i32 v[82:83], s[14:15], v46, s16, v[48:49]
	v_cmp_gt_u32_e64 s[2:3], 16, v11
	v_add_u32_e32 v54, s4, v50
	v_cmp_eq_u32_e64 s[4:5], 0, v11
	v_cmp_gt_u32_e64 s[6:7], 2, v11
	v_cmp_gt_u32_e64 s[8:9], 4, v11
	v_cmp_gt_u32_e64 s[10:11], 8, v11
	v_cmp_gt_u32_e64 s[12:13], 32, v11
	v_lshl_or_b32 v80, s30, 2, v1
	v_lshrrev_b32_e32 v1, 1, v11
	s_mul_i32 s14, s0, 0xc00000
	v_mad_i64_i32 v[10:11], s[30:31], v10, s38, 0
	v_mad_i64_i32 v[84:85], s[30:31], s0, v116, v[10:11]
	s_or_b32 s14, s14, s65
	s_mul_hi_i32 s15, s0, 0xc00000
	s_add_u32 s30, s14, 0xedc0000
	s_addc_u32 s31, s15, 0
	v_mov_b64_e32 v[10:11], s[30:31]
	v_mad_i64_i32 v[86:87], s[30:31], v0, s38, v[10:11]
	v_and_b32_e32 v0, 3, v3
	v_lshlrev_b32_e32 v0, 4, v0
	v_and_b32_e32 v48, 24, v1
	v_or3_b32 v86, v86, s66, v0
	v_mov_b64_e32 v[0:1], s[14:15]
	v_mul_u32_u24_e32 v51, 0x110, v70
	v_mul_u32_u24_e32 v50, 0x110, v47
	v_mul_u32_u24_e32 v60, 0x50, v47
	s_lshl_b64 s[30:31], s[0:1], 13
	v_ashrrev_i32_e32 v47, 31, v46
	v_mad_i64_i32 v[90:91], s[14:15], v46, s38, v[0:1]
	v_lshl_add_u32 v129, v46, 2, s89
	v_sub_u32_e32 v130, v46, v76
	s_waitcnt vmcnt(11)
	v_mov_b32_e32 v69, v68
	v_or3_b32 v82, v82, s66, v48
	v_or3_b32 v84, v84, s67, v44
	v_lshl_add_u64 v[88:89], v[46:47], 2, s[30:31]
	v_or3_b32 v90, v90, s66, v48
	s_mov_b32 s1, 15
	v_add_u32_e32 v156, v45, v51
	v_add_u32_e32 v157, v52, v9
	v_add_u32_e32 v158, v53, v55
	v_add_u32_e32 v159, v52, v56
	v_add_u32_e32 v160, v53, v57
	v_add_u32_e32 v161, v52, v58
	v_add_u32_e32 v162, v53, v59
	v_add_u32_e32 v163, v52, v50
	v_add_u32_e32 v164, v53, v60
	v_add_u32_e32 v165, v54, v51
	v_mov_b32_e32 v9, v8
	v_mov_b32_e32 v10, v8
	v_mov_b32_e32 v11, v8
	v_mov_b32_e32 v44, v8
	v_mov_b32_e32 v45, v8
	v_mov_b32_e32 v46, v8
	v_mov_b32_e32 v47, v8
	v_mov_b32_e32 v234, 0x193fc
	s_lshr_b32 s30, s61, 6
	s_lshl_b32 s30, s30, 18
	s_lshl_b32 s31, s64, 15
	s_add_i32 s30, s30, s31
	s_lshl_b32 s31, s62, 2
	s_add_i32 s30, s30, s31
	v_lshl_add_u32 v194, v73, 7, s30
	v_add_u32_e32 v195, 0x2000, v194
	s_add_u32 s14, s92, 0xeb00000
	s_addc_u32 s15, s93, 0
	s_mul_i32 s30, s64, 0xc00
	v_add_u32_e32 v122, s30, v122
	v_add_u32_e32 v123, s30, v123
	v_add_u32_e32 v124, s30, v124
	v_add_u32_e32 v125, s30, v125
	v_add_u32_e32 v126, s30, v126
	v_add_u32_e32 v127, s30, v127
	global_load_dword v77, v194, s[14:15]
	global_load_dword v120, v195, s[14:15]
	s_waitcnt vmcnt(0)
	v_add_f32_e32 v0, v71, v77
	v_cmp_nlt_f32_e32 vcc, s76, v0
	s_and_saveexec_b64 s[30:31], vcc
	s_cbranch_execz .Lscanprea_469
	v_mul_f32_e32 v0, 0x3fb8aa3b, v0
	v_exp_f32_e32 v3, v0
	s_nop 0
	v_add_f32_e32 v48, 1.0, v3
	v_frexp_mant_f32_e32 v50, v48
	v_cvt_f64_f32_e32 v[0:1], v48
	v_frexp_exp_i32_f64_e32 v0, v[0:1]
	v_cmp_gt_f32_e32 vcc, s77, v50
	v_add_f32_e32 v49, -1.0, v48
	v_sub_f32_e32 v51, v49, v48
	v_subbrev_co_u32_e32 v54, vcc, 0, v0, vcc
	v_sub_u32_e32 v0, 0, v54
	v_sub_f32_e32 v49, v3, v49
	v_add_f32_e32 v51, 1.0, v51
	v_ldexp_f32 v1, v48, v0
	v_add_f32_e32 v49, v49, v51
	v_add_f32_e32 v48, -1.0, v1
	v_add_f32_e32 v50, 1.0, v1
	v_ldexp_f32 v0, v49, v0
	v_add_f32_e32 v49, 1.0, v48
	v_add_f32_e32 v51, -1.0, v50
	v_sub_f32_e32 v49, v1, v49
	v_sub_f32_e32 v1, v1, v51
	v_add_f32_e32 v49, v0, v49
	v_add_f32_e32 v0, v0, v1
	v_add_f32_e32 v55, v50, v0
	v_rcp_f32_e32 v57, v55
	v_sub_f32_e32 v1, v55, v50
	v_sub_f32_e32 v56, v0, v1
	v_add_f32_e32 v1, v48, v49
	v_mul_f32_e32 v59, v1, v57
	v_sub_f32_e32 v0, v1, v48
	v_mul_f32_e32 v48, v55, v59
	v_fma_f32 v50, v59, v55, -v48
	v_fmac_f32_e32 v50, v59, v56
	v_sub_f32_e32 v58, v49, v0
	v_add_f32_e32 v0, v48, v50
	v_sub_f32_e32 v49, v1, v0
	v_pk_add_f32 v[52:53], v[0:1], v[48:49] neg_lo:[0,1] neg_hi:[0,1]
	v_mov_b32_e32 v51, v0
	v_pk_add_f32 v[0:1], v[52:53], v[50:51] neg_lo:[0,1] neg_hi:[0,1]
	v_cmp_neq_f32_e32 vcc, s80, v3
	v_add_f32_e32 v1, v58, v1
	v_add_f32_e32 v0, v0, v1
	v_add_f32_e32 v1, v49, v0
	v_mul_f32_e32 v58, v57, v1
	v_mul_f32_e32 v48, v55, v58
	v_fma_f32 v50, v58, v55, -v48
	v_fmac_f32_e32 v50, v58, v56
	v_sub_f32_e32 v49, v49, v1
	v_add_f32_e32 v55, v0, v49
	v_add_f32_e32 v0, v48, v50
	v_sub_f32_e32 v49, v1, v0
	v_pk_add_f32 v[52:53], v[0:1], v[48:49] neg_lo:[0,1] neg_hi:[0,1]
	v_mov_b32_e32 v51, v0
	v_pk_add_f32 v[0:1], v[52:53], v[50:51] neg_lo:[0,1] neg_hi:[0,1]
	s_nop 0
	v_add_f32_e32 v1, v55, v1
	v_add_f32_e32 v0, v0, v1
	v_add_f32_e32 v1, v59, v58
	v_add_f32_e32 v0, v49, v0
	v_sub_f32_e32 v48, v1, v59
	v_mul_f32_e32 v0, v57, v0
	v_sub_f32_e32 v48, v58, v48
	v_add_f32_e32 v48, v48, v0
	v_add_f32_e32 v50, v1, v48
	v_mul_f32_e32 v51, v50, v50
	v_fmamk_f32 v0, v51, 0x3e9b6dac, v110
	v_fmaak_f32 v75, v51, v0, 0x3f2aaada
	v_cvt_f32_i32_e32 v0, v54
	v_sub_f32_e32 v1, v50, v1
	v_sub_f32_e32 v1, v48, v1
	v_ldexp_f32 v52, v1, 1
	v_mul_f32_e32 v1, v50, v51
	v_ldexp_f32 v49, v50, 1
	v_pk_mul_f32 v[50:51], v[0:1], v[74:75]
	s_nop 0
	v_fma_f32 v48, v0, s33, -v50
	v_fmac_f32_e32 v48, 0xb102e308, v0
	v_pk_add_f32 v[0:1], v[50:51], v[48:49]
	s_nop 0
	v_sub_f32_e32 v49, v1, v49
	v_sub_f32_e32 v49, v51, v49
	v_add_f32_e32 v53, v52, v49
	v_mov_b32_e32 v52, v50
	v_pk_add_f32 v[50:51], v[0:1], v[50:51] neg_lo:[0,1] neg_hi:[0,1]
	v_pk_add_f32 v[54:55], v[0:1], v[52:53]
	v_mov_b32_e32 v49, v0
	v_mov_b32_e32 v51, v55
	v_pk_add_f32 v[56:57], v[48:49], v[50:51] neg_lo:[0,1] neg_hi:[0,1]
	v_pk_add_f32 v[48:49], v[48:49], v[50:51]
	v_mov_b32_e32 v52, v53
	v_pk_add_f32 v[50:51], v[48:49], v[0:1] op_sel:[1,0] op_sel_hi:[0,1] neg_lo:[0,1] neg_hi:[0,1]
	v_pk_add_f32 v[58:59], v[54:55], v[50:51] op_sel_hi:[1,0] neg_lo:[0,1] neg_hi:[0,1]
	v_mov_b32_e32 v54, v55
	v_mov_b32_e32 v55, v49
	v_pk_mov_b32 v[50:51], v[0:1], v[50:51] op_sel:[1,0]
	v_mov_b32_e32 v53, v0
	v_pk_add_f32 v[50:51], v[54:55], v[50:51] neg_lo:[0,1] neg_hi:[0,1]
	v_mov_b32_e32 v58, v56
	v_pk_add_f32 v[0:1], v[52:53], v[50:51] neg_lo:[0,1] neg_hi:[0,1]
	v_mov_b32_e32 v57, v49
	v_pk_add_f32 v[50:51], v[58:59], v[0:1]
	s_nop 0
	v_pk_add_f32 v[52:53], v[50:51], v[50:51] op_sel:[0,1] op_sel_hi:[1,0]
	s_nop 0
	v_pk_add_f32 v[48:49], v[48:49], v[52:53] op_sel:[1,0] op_sel_hi:[0,1]
	v_mov_b32_e32 v51, v48
	v_pk_add_f32 v[54:55], v[50:51], v[56:57] neg_lo:[0,1] neg_hi:[0,1]
	v_mov_b32_e32 v1, v52
	v_sub_f32_e32 v49, v50, v54
	v_pk_add_f32 v[0:1], v[0:1], v[54:55] neg_lo:[0,1] neg_hi:[0,1]
	v_sub_f32_e32 v49, v56, v49
	v_add_f32_e32 v0, v0, v49
	v_add_f32_e32 v0, v0, v1
	v_add_f32_e32 v0, v48, v0
	v_cndmask_b32_e32 v0, v112, v0, vcc
	v_cmp_ngt_f32_e32 vcc, -1.0, v3
	s_nop 1
	v_cndmask_b32_e32 v0, v113, v0, vcc
	v_cmp_neq_f32_e32 vcc, -1.0, v3
	s_nop 1
	v_cndmask_b32_e32 v0, v114, v0, vcc
	v_cmp_lt_f32_e64 vcc, |v3|, s81
	s_nop 1
	v_cndmask_b32_e32 v0, v0, v3, vcc
.Lscanprea_469:
	s_or_b64 exec, exec, s[30:31]
	v_add_f32_e32 v1, v71, v120
	v_cmp_nlt_f32_e32 vcc, s76, v1
	s_and_saveexec_b64 s[30:31], vcc
	s_cbranch_execz .Lscanprea_471
	v_mul_f32_e32 v1, 0x3fb8aa3b, v1
	v_exp_f32_e32 v1, v1
	s_nop 0
	v_add_f32_e32 v3, 1.0, v1
	v_frexp_mant_f32_e32 v51, v3
	v_cvt_f64_f32_e32 v[48:49], v3
	v_add_f32_e32 v50, -1.0, v3
	v_frexp_exp_i32_f64_e32 v48, v[48:49]
	v_cmp_gt_f32_e32 vcc, s77, v51
	v_sub_f32_e32 v52, v50, v3
	v_sub_f32_e32 v50, v1, v50
	v_subbrev_co_u32_e32 v56, vcc, 0, v48, vcc
	v_add_f32_e32 v52, 1.0, v52
	v_sub_u32_e32 v48, 0, v56
	v_add_f32_e32 v50, v50, v52
	v_ldexp_f32 v3, v3, v48
	v_ldexp_f32 v48, v50, v48
	v_add_f32_e32 v50, -1.0, v3
	v_add_f32_e32 v49, 1.0, v50
	v_sub_f32_e32 v49, v3, v49
	v_add_f32_e32 v51, v48, v49
	v_add_f32_e32 v49, 1.0, v3
	v_add_f32_e32 v52, -1.0, v49
	v_sub_f32_e32 v3, v3, v52
	v_add_f32_e32 v3, v48, v3
	v_add_f32_e32 v57, v49, v3
	v_rcp_f32_e32 v58, v57
	v_sub_f32_e32 v48, v57, v49
	v_add_f32_e32 v49, v50, v51
	v_sub_f32_e32 v3, v3, v48
	v_mul_f32_e32 v60, v49, v58
	v_sub_f32_e32 v48, v49, v50
	v_mul_f32_e32 v50, v57, v60
	v_fma_f32 v52, v60, v57, -v50
	v_fmac_f32_e32 v52, v60, v3
	v_sub_f32_e32 v59, v51, v48
	v_add_f32_e32 v48, v50, v52
	v_sub_f32_e32 v51, v49, v48
	v_pk_add_f32 v[54:55], v[48:49], v[50:51] neg_lo:[0,1] neg_hi:[0,1]
	v_mov_b32_e32 v53, v48
	v_pk_add_f32 v[48:49], v[54:55], v[52:53] neg_lo:[0,1] neg_hi:[0,1]
	v_cmp_neq_f32_e32 vcc, s80, v1
	v_add_f32_e32 v49, v59, v49
	v_add_f32_e32 v48, v48, v49
	v_add_f32_e32 v49, v51, v48
	v_mul_f32_e32 v59, v58, v49
	v_mul_f32_e32 v50, v57, v59
	v_fma_f32 v52, v59, v57, -v50
	v_fmac_f32_e32 v52, v59, v3
	v_sub_f32_e32 v3, v51, v49
	v_add_f32_e32 v3, v48, v3
	v_add_f32_e32 v48, v50, v52
	v_sub_f32_e32 v51, v49, v48
	v_pk_add_f32 v[54:55], v[48:49], v[50:51] neg_lo:[0,1] neg_hi:[0,1]
	v_mov_b32_e32 v53, v48
	v_pk_add_f32 v[48:49], v[54:55], v[52:53] neg_lo:[0,1] neg_hi:[0,1]
	s_nop 0
	v_add_f32_e32 v3, v3, v49
	v_add_f32_e32 v3, v48, v3
	v_add_f32_e32 v49, v60, v59
	v_add_f32_e32 v3, v51, v3
	v_sub_f32_e32 v48, v49, v60
	v_mul_f32_e32 v3, v58, v3
	v_sub_f32_e32 v48, v59, v48
	v_add_f32_e32 v3, v48, v3
	v_add_f32_e32 v50, v49, v3
	v_mul_f32_e32 v52, v50, v50
	v_fmamk_f32 v48, v52, 0x3e9b6dac, v110
	v_fmaak_f32 v75, v52, v48, 0x3f2aaada
	v_cvt_f32_i32_e32 v48, v56
	v_sub_f32_e32 v49, v50, v49
	v_sub_f32_e32 v3, v3, v49
	v_mul_f32_e32 v49, v50, v52
	v_pk_mul_f32 v[52:53], v[48:49], v[74:75]
	v_ldexp_f32 v51, v50, 1
	v_fma_f32 v50, v48, s33, -v52
	v_fmac_f32_e32 v50, 0xb102e308, v48
	v_pk_add_f32 v[48:49], v[52:53], v[50:51]
	v_ldexp_f32 v3, v3, 1
	v_sub_f32_e32 v51, v49, v51
	v_sub_f32_e32 v51, v53, v51
	v_add_f32_e32 v55, v3, v51
	v_mov_b32_e32 v54, v52
	v_pk_add_f32 v[52:53], v[48:49], v[52:53] neg_lo:[0,1] neg_hi:[0,1]
	v_pk_add_f32 v[56:57], v[48:49], v[54:55]
	v_mov_b32_e32 v51, v48
	v_mov_b32_e32 v53, v57
	v_pk_add_f32 v[58:59], v[50:51], v[52:53] neg_lo:[0,1] neg_hi:[0,1]
	v_pk_add_f32 v[50:51], v[50:51], v[52:53]
	v_mov_b32_e32 v54, v55
	v_pk_add_f32 v[52:53], v[50:51], v[48:49] op_sel:[1,0] op_sel_hi:[0,1] neg_lo:[0,1] neg_hi:[0,1]
	v_pk_add_f32 v[60:61], v[56:57], v[52:53] op_sel_hi:[1,0] neg_lo:[0,1] neg_hi:[0,1]
	v_mov_b32_e32 v56, v57
	v_mov_b32_e32 v57, v51
	v_pk_mov_b32 v[52:53], v[48:49], v[52:53] op_sel:[1,0]
	v_mov_b32_e32 v55, v48
	v_pk_add_f32 v[52:53], v[56:57], v[52:53] neg_lo:[0,1] neg_hi:[0,1]
	v_mov_b32_e32 v60, v58
	v_pk_add_f32 v[48:49], v[54:55], v[52:53] neg_lo:[0,1] neg_hi:[0,1]
	v_mov_b32_e32 v59, v51
	v_pk_add_f32 v[52:53], v[60:61], v[48:49]
	s_nop 0
	v_pk_add_f32 v[54:55], v[52:53], v[52:53] op_sel:[0,1] op_sel_hi:[1,0]
	s_nop 0
	v_pk_add_f32 v[50:51], v[50:51], v[54:55] op_sel:[1,0] op_sel_hi:[0,1]
	v_mov_b32_e32 v53, v50
	v_pk_add_f32 v[56:57], v[52:53], v[58:59] neg_lo:[0,1] neg_hi:[0,1]
	v_mov_b32_e32 v49, v54
	v_sub_f32_e32 v3, v52, v56
	v_pk_add_f32 v[48:49], v[48:49], v[56:57] neg_lo:[0,1] neg_hi:[0,1]
	v_sub_f32_e32 v3, v58, v3
	v_add_f32_e32 v3, v48, v3
	v_add_f32_e32 v3, v3, v49
	v_add_f32_e32 v3, v50, v3
	v_cndmask_b32_e32 v3, v112, v3, vcc
	v_cmp_ngt_f32_e32 vcc, -1.0, v1
	s_nop 1
	v_cndmask_b32_e32 v3, v113, v3, vcc
	v_cmp_neq_f32_e32 vcc, -1.0, v1
	s_nop 1
	v_cndmask_b32_e32 v3, v114, v3, vcc
	v_cmp_lt_f32_e64 vcc, |v1|, s81
	s_nop 1
	v_cndmask_b32_e32 v1, v3, v1, vcc
.Lscanprea_471:
	s_or_b64 exec, exec, s[30:31]
	v_and_b32_e32 v3, 64, v73
	v_add_u32_e32 v48, -1, v73
	v_cmp_lt_i32_e32 vcc, v48, v3
	v_add_u32_e32 v50, -2, v73
	v_cndmask_b32_e32 v48, v48, v73, vcc
	v_lshlrev_b32_e32 v48, 2, v48
	ds_bpermute_b32 v49, v48, v0
	ds_bpermute_b32 v48, v48, v1
	v_cmp_lt_i32_e32 vcc, v50, v3
	s_waitcnt lgkmcnt(1)
	v_add_f32_e32 v49, v0, v49
	s_waitcnt lgkmcnt(0)
	v_add_f32_e32 v48, v1, v48
	v_cndmask_b32_e32 v50, v50, v73, vcc
	v_cndmask_b32_e64 v48, v48, v1, s[4:5]
	v_cndmask_b32_e64 v49, v49, v0, s[4:5]
	v_lshlrev_b32_e32 v50, 2, v50
	ds_bpermute_b32 v51, v50, v49
	ds_bpermute_b32 v50, v50, v48
	s_waitcnt lgkmcnt(1)
	v_add_f32_e32 v51, v49, v51
	s_waitcnt lgkmcnt(0)
	v_add_f32_e32 v50, v48, v50
	v_cndmask_b32_e64 v48, v50, v48, s[6:7]
	v_add_u32_e32 v50, -4, v73
	v_cmp_lt_i32_e32 vcc, v50, v3
	v_cndmask_b32_e64 v49, v51, v49, s[6:7]
	s_nop 0
	v_cndmask_b32_e32 v50, v50, v73, vcc
	v_lshlrev_b32_e32 v50, 2, v50
	ds_bpermute_b32 v51, v50, v49
	ds_bpermute_b32 v50, v50, v48
	s_waitcnt lgkmcnt(1)
	v_add_f32_e32 v51, v49, v51
	s_waitcnt lgkmcnt(0)
	v_add_f32_e32 v50, v48, v50
	v_cndmask_b32_e64 v48, v50, v48, s[8:9]
	v_add_u32_e32 v50, -8, v73
	v_cmp_lt_i32_e32 vcc, v50, v3
	v_cndmask_b32_e64 v49, v51, v49, s[8:9]
	s_nop 0
	v_cndmask_b32_e32 v50, v50, v73, vcc
	v_lshlrev_b32_e32 v50, 2, v50
	ds_bpermute_b32 v51, v50, v49
	ds_bpermute_b32 v50, v50, v48
	s_waitcnt lgkmcnt(1)
	v_add_f32_e32 v51, v49, v51
	s_waitcnt lgkmcnt(0)
	v_add_f32_e32 v50, v48, v50
	v_cndmask_b32_e64 v48, v50, v48, s[10:11]
	v_add_u32_e32 v50, -16, v73
	v_cmp_lt_i32_e32 vcc, v50, v3
	v_cndmask_b32_e64 v49, v51, v49, s[10:11]
	s_nop 0
	v_cndmask_b32_e32 v50, v50, v73, vcc
	v_lshlrev_b32_e32 v50, 2, v50
	ds_bpermute_b32 v51, v50, v49
	ds_bpermute_b32 v50, v50, v48
	s_waitcnt lgkmcnt(1)
	v_add_f32_e32 v51, v49, v51
	s_waitcnt lgkmcnt(0)
	v_add_f32_e32 v50, v48, v50
	v_cndmask_b32_e64 v48, v50, v48, s[2:3]
	v_cndmask_b32_e64 v50, v51, v49, s[2:3]
	v_subrev_u32_e32 v49, 32, v73
	v_cmp_lt_i32_e32 vcc, v49, v3
	s_nop 1
	v_cndmask_b32_e32 v3, v49, v73, vcc
	v_lshlrev_b32_e32 v3, 2, v3
	ds_bpermute_b32 v49, v3, v50
	ds_bpermute_b32 v3, v3, v48
	s_waitcnt lgkmcnt(1)
	v_add_f32_e32 v51, v50, v49
	s_waitcnt lgkmcnt(0)
	v_add_f32_e32 v3, v48, v3
	v_cndmask_b32_e64 v49, v3, v48, s[12:13]
	v_cndmask_b32_e64 v3, v51, v50, s[12:13]
	v_lshl_or_b32 v48, v73, 2, v117
	ds_bpermute_b32 v50, v48, v3
	ds_bpermute_b32 v48, v48, v49
	s_waitcnt lgkmcnt(0)
	v_add_f32_e32 v48, v50, v48
	v_sub_f32_e32 v51, v48, v50
	v_sub_f32_e32 v51, v51, v49
	v_mul_f32_e32 v51, v51, v119
	v_mul_f32_e32 v51, 0xbfb8aa3b, v51
	v_exp_f32_e32 v51, v51
	v_add_f32_e32 v49, v49, v50
	ds_write_b32 v122, v1
	v_mul_f32_e64 v49, v49, -v119
	v_mul_f32_e32 v1, v1, v51
	ds_write_b32 v123, v49
	ds_write_b32 v124, v1
	v_sub_f32_e32 v1, v48, v3
	v_mul_f32_e32 v1, v1, v119
	v_mul_f32_e32 v1, 0xbfb8aa3b, v1
	v_exp_f32_e32 v1, v1
	ds_write_b32 v125, v0
	v_mul_f32_e64 v3, v3, -v119
	ds_write_b32 v126, v3
	v_mul_f32_e32 v0, v0, v1
	ds_write_b32 v127, v0
	v_add_u32_e32 v194, 0x4000, v194
	v_add_u32_e32 v195, 0x4000, v195
	v_add_u32_e32 v122, 0x600, v122
	v_add_u32_e32 v123, 0x600, v123
	v_add_u32_e32 v124, 0x600, v124
	v_add_u32_e32 v125, 0x600, v125
	v_add_u32_e32 v126, 0x600, v126
	v_add_u32_e32 v127, 0x600, v127
	global_load_dword v77, v194, s[14:15]
	global_load_dword v120, v195, s[14:15]
	s_waitcnt vmcnt(0)
	v_add_f32_e32 v0, v71, v77
	v_cmp_nlt_f32_e32 vcc, s76, v0
	s_and_saveexec_b64 s[30:31], vcc
	s_cbranch_execz .Lscanpreb_469
	v_mul_f32_e32 v0, 0x3fb8aa3b, v0
	v_exp_f32_e32 v3, v0
	s_nop 0
	v_add_f32_e32 v48, 1.0, v3
	v_frexp_mant_f32_e32 v50, v48
	v_cvt_f64_f32_e32 v[0:1], v48
	v_frexp_exp_i32_f64_e32 v0, v[0:1]
	v_cmp_gt_f32_e32 vcc, s77, v50
	v_add_f32_e32 v49, -1.0, v48
	v_sub_f32_e32 v51, v49, v48
	v_subbrev_co_u32_e32 v54, vcc, 0, v0, vcc
	v_sub_u32_e32 v0, 0, v54
	v_sub_f32_e32 v49, v3, v49
	v_add_f32_e32 v51, 1.0, v51
	v_ldexp_f32 v1, v48, v0
	v_add_f32_e32 v49, v49, v51
	v_add_f32_e32 v48, -1.0, v1
	v_add_f32_e32 v50, 1.0, v1
	v_ldexp_f32 v0, v49, v0
	v_add_f32_e32 v49, 1.0, v48
	v_add_f32_e32 v51, -1.0, v50
	v_sub_f32_e32 v49, v1, v49
	v_sub_f32_e32 v1, v1, v51
	v_add_f32_e32 v49, v0, v49
	v_add_f32_e32 v0, v0, v1
	v_add_f32_e32 v55, v50, v0
	v_rcp_f32_e32 v57, v55
	v_sub_f32_e32 v1, v55, v50
	v_sub_f32_e32 v56, v0, v1
	v_add_f32_e32 v1, v48, v49
	v_mul_f32_e32 v59, v1, v57
	v_sub_f32_e32 v0, v1, v48
	v_mul_f32_e32 v48, v55, v59
	v_fma_f32 v50, v59, v55, -v48
	v_fmac_f32_e32 v50, v59, v56
	v_sub_f32_e32 v58, v49, v0
	v_add_f32_e32 v0, v48, v50
	v_sub_f32_e32 v49, v1, v0
	v_pk_add_f32 v[52:53], v[0:1], v[48:49] neg_lo:[0,1] neg_hi:[0,1]
	v_mov_b32_e32 v51, v0
	v_pk_add_f32 v[0:1], v[52:53], v[50:51] neg_lo:[0,1] neg_hi:[0,1]
	v_cmp_neq_f32_e32 vcc, s80, v3
	v_add_f32_e32 v1, v58, v1
	v_add_f32_e32 v0, v0, v1
	v_add_f32_e32 v1, v49, v0
	v_mul_f32_e32 v58, v57, v1
	v_mul_f32_e32 v48, v55, v58
	v_fma_f32 v50, v58, v55, -v48
	v_fmac_f32_e32 v50, v58, v56
	v_sub_f32_e32 v49, v49, v1
	v_add_f32_e32 v55, v0, v49
	v_add_f32_e32 v0, v48, v50
	v_sub_f32_e32 v49, v1, v0
	v_pk_add_f32 v[52:53], v[0:1], v[48:49] neg_lo:[0,1] neg_hi:[0,1]
	v_mov_b32_e32 v51, v0
	v_pk_add_f32 v[0:1], v[52:53], v[50:51] neg_lo:[0,1] neg_hi:[0,1]
	s_nop 0
	v_add_f32_e32 v1, v55, v1
	v_add_f32_e32 v0, v0, v1
	v_add_f32_e32 v1, v59, v58
	v_add_f32_e32 v0, v49, v0
	v_sub_f32_e32 v48, v1, v59
	v_mul_f32_e32 v0, v57, v0
	v_sub_f32_e32 v48, v58, v48
	v_add_f32_e32 v48, v48, v0
	v_add_f32_e32 v50, v1, v48
	v_mul_f32_e32 v51, v50, v50
	v_fmamk_f32 v0, v51, 0x3e9b6dac, v110
	v_fmaak_f32 v75, v51, v0, 0x3f2aaada
	v_cvt_f32_i32_e32 v0, v54
	v_sub_f32_e32 v1, v50, v1
	v_sub_f32_e32 v1, v48, v1
	v_ldexp_f32 v52, v1, 1
	v_mul_f32_e32 v1, v50, v51
	v_ldexp_f32 v49, v50, 1
	v_pk_mul_f32 v[50:51], v[0:1], v[74:75]
	s_nop 0
	v_fma_f32 v48, v0, s33, -v50
	v_fmac_f32_e32 v48, 0xb102e308, v0
	v_pk_add_f32 v[0:1], v[50:51], v[48:49]
	s_nop 0
	v_sub_f32_e32 v49, v1, v49
	v_sub_f32_e32 v49, v51, v49
	v_add_f32_e32 v53, v52, v49
	v_mov_b32_e32 v52, v50
	v_pk_add_f32 v[50:51], v[0:1], v[50:51] neg_lo:[0,1] neg_hi:[0,1]
	v_pk_add_f32 v[54:55], v[0:1], v[52:53]
	v_mov_b32_e32 v49, v0
	v_mov_b32_e32 v51, v55
	v_pk_add_f32 v[56:57], v[48:49], v[50:51] neg_lo:[0,1] neg_hi:[0,1]
	v_pk_add_f32 v[48:49], v[48:49], v[50:51]
	v_mov_b32_e32 v52, v53
	v_pk_add_f32 v[50:51], v[48:49], v[0:1] op_sel:[1,0] op_sel_hi:[0,1] neg_lo:[0,1] neg_hi:[0,1]
	v_pk_add_f32 v[58:59], v[54:55], v[50:51] op_sel_hi:[1,0] neg_lo:[0,1] neg_hi:[0,1]
	v_mov_b32_e32 v54, v55
	v_mov_b32_e32 v55, v49
	v_pk_mov_b32 v[50:51], v[0:1], v[50:51] op_sel:[1,0]
	v_mov_b32_e32 v53, v0
	v_pk_add_f32 v[50:51], v[54:55], v[50:51] neg_lo:[0,1] neg_hi:[0,1]
	v_mov_b32_e32 v58, v56
	v_pk_add_f32 v[0:1], v[52:53], v[50:51] neg_lo:[0,1] neg_hi:[0,1]
	v_mov_b32_e32 v57, v49
	v_pk_add_f32 v[50:51], v[58:59], v[0:1]
	s_nop 0
	v_pk_add_f32 v[52:53], v[50:51], v[50:51] op_sel:[0,1] op_sel_hi:[1,0]
	s_nop 0
	v_pk_add_f32 v[48:49], v[48:49], v[52:53] op_sel:[1,0] op_sel_hi:[0,1]
	v_mov_b32_e32 v51, v48
	v_pk_add_f32 v[54:55], v[50:51], v[56:57] neg_lo:[0,1] neg_hi:[0,1]
	v_mov_b32_e32 v1, v52
	v_sub_f32_e32 v49, v50, v54
	v_pk_add_f32 v[0:1], v[0:1], v[54:55] neg_lo:[0,1] neg_hi:[0,1]
	v_sub_f32_e32 v49, v56, v49
	v_add_f32_e32 v0, v0, v49
	v_add_f32_e32 v0, v0, v1
	v_add_f32_e32 v0, v48, v0
	v_cndmask_b32_e32 v0, v112, v0, vcc
	v_cmp_ngt_f32_e32 vcc, -1.0, v3
	s_nop 1
	v_cndmask_b32_e32 v0, v113, v0, vcc
	v_cmp_neq_f32_e32 vcc, -1.0, v3
	s_nop 1
	v_cndmask_b32_e32 v0, v114, v0, vcc
	v_cmp_lt_f32_e64 vcc, |v3|, s81
	s_nop 1
	v_cndmask_b32_e32 v0, v0, v3, vcc

.Lscanpreb_471:
	s_or_b64 exec, exec, s[30:31]
	v_and_b32_e32 v3, 64, v73
	v_add_u32_e32 v48, -1, v73
	v_cmp_lt_i32_e32 vcc, v48, v3
	v_add_u32_e32 v50, -2, v73
	v_cndmask_b32_e32 v48, v48, v73, vcc
	v_lshlrev_b32_e32 v48, 2, v48
	ds_bpermute_b32 v49, v48, v0
	ds_bpermute_b32 v48, v48, v1
	v_cmp_lt_i32_e32 vcc, v50, v3
	s_waitcnt lgkmcnt(1)
	v_add_f32_e32 v49, v0, v49
	s_waitcnt lgkmcnt(0)
	v_add_f32_e32 v48, v1, v48
	v_cndmask_b32_e32 v50, v50, v73, vcc
	v_cndmask_b32_e64 v48, v48, v1, s[4:5]
	v_cndmask_b32_e64 v49, v49, v0, s[4:5]
	v_lshlrev_b32_e32 v50, 2, v50
	ds_bpermute_b32 v51, v50, v49
	ds_bpermute_b32 v50, v50, v48
	s_waitcnt lgkmcnt(1)
	v_add_f32_e32 v51, v49, v51
	s_waitcnt lgkmcnt(0)
	v_add_f32_e32 v50, v48, v50
	v_cndmask_b32_e64 v48, v50, v48, s[6:7]
	v_add_u32_e32 v50, -4, v73
	v_cmp_lt_i32_e32 vcc, v50, v3
	v_cndmask_b32_e64 v49, v51, v49, s[6:7]
	s_nop 0
	v_cndmask_b32_e32 v50, v50, v73, vcc
	v_lshlrev_b32_e32 v50, 2, v50
	ds_bpermute_b32 v51, v50, v49
	ds_bpermute_b32 v50, v50, v48
	s_waitcnt lgkmcnt(1)
	v_add_f32_e32 v51, v49, v51
	s_waitcnt lgkmcnt(0)
	v_add_f32_e32 v50, v48, v50
	v_cndmask_b32_e64 v48, v50, v48, s[8:9]
	v_add_u32_e32 v50, -8, v73
	v_cmp_lt_i32_e32 vcc, v50, v3
	v_cndmask_b32_e64 v49, v51, v49, s[8:9]
	s_nop 0
	v_cndmask_b32_e32 v50, v50, v73, vcc
	v_lshlrev_b32_e32 v50, 2, v50
	ds_bpermute_b32 v51, v50, v49
	ds_bpermute_b32 v50, v50, v48
	s_waitcnt lgkmcnt(1)
	v_add_f32_e32 v51, v49, v51
	s_waitcnt lgkmcnt(0)
	v_add_f32_e32 v50, v48, v50
	v_cndmask_b32_e64 v48, v50, v48, s[10:11]
	v_add_u32_e32 v50, -16, v73
	v_cmp_lt_i32_e32 vcc, v50, v3
	v_cndmask_b32_e64 v49, v51, v49, s[10:11]
	s_nop 0
	v_cndmask_b32_e32 v50, v50, v73, vcc
	v_lshlrev_b32_e32 v50, 2, v50
	ds_bpermute_b32 v51, v50, v49
	ds_bpermute_b32 v50, v50, v48
	s_waitcnt lgkmcnt(1)
	v_add_f32_e32 v51, v49, v51
	s_waitcnt lgkmcnt(0)
	v_add_f32_e32 v50, v48, v50
	v_cndmask_b32_e64 v48, v50, v48, s[2:3]
	v_cndmask_b32_e64 v50, v51, v49, s[2:3]
	v_subrev_u32_e32 v49, 32, v73
	v_cmp_lt_i32_e32 vcc, v49, v3
	s_nop 1
	v_cndmask_b32_e32 v3, v49, v73, vcc
	v_lshlrev_b32_e32 v3, 2, v3
	ds_bpermute_b32 v49, v3, v50
	ds_bpermute_b32 v3, v3, v48
	s_waitcnt lgkmcnt(1)
	v_add_f32_e32 v51, v50, v49
	s_waitcnt lgkmcnt(0)
	v_add_f32_e32 v3, v48, v3
	v_cndmask_b32_e64 v49, v3, v48, s[12:13]
	v_cndmask_b32_e64 v3, v51, v50, s[12:13]
	v_lshl_or_b32 v48, v73, 2, v117
	ds_bpermute_b32 v50, v48, v3
	ds_bpermute_b32 v48, v48, v49
	s_waitcnt lgkmcnt(0)
	v_add_f32_e32 v48, v50, v48
	v_sub_f32_e32 v51, v48, v50
	v_sub_f32_e32 v51, v51, v49
	v_mul_f32_e32 v51, v51, v119
	v_mul_f32_e32 v51, 0xbfb8aa3b, v51
	v_exp_f32_e32 v51, v51
	v_add_f32_e32 v49, v49, v50
	ds_write_b32 v122, v1
	v_mul_f32_e64 v49, v49, -v119
	v_mul_f32_e32 v1, v1, v51
	ds_write_b32 v123, v49
	ds_write_b32 v124, v1
	v_sub_f32_e32 v1, v48, v3
	v_mul_f32_e32 v1, v1, v119
	v_mul_f32_e32 v1, 0xbfb8aa3b, v1
	v_exp_f32_e32 v1, v1
	ds_write_b32 v125, v0
	v_mul_f32_e64 v3, v3, -v119
	ds_write_b32 v126, v3
	v_mul_f32_e32 v0, v0, v1
	ds_write_b32 v127, v0
	s_branch .LBB0_466
.LBB0_465:
	s_or_b64 exec, exec, s[14:15]
	s_waitcnt lgkmcnt(0)
	ds_read_b64_tr_b16 v[48:49], v157 offset:34816
	ds_read_b128 v[194:197], v152
	ds_read_b128 v[198:201], v152 offset:16
	ds_read_b64_tr_b16 v[62:63], v158 offset:320
	ds_read_b64_tr_b16 v[60:61], v158
	ds_read_b64_tr_b16 v[64:65], v158 offset:32
	ds_read_b64_tr_b16 v[50:51], v157 offset:35904
	s_waitcnt lgkmcnt(2)
	v_lshlrev_b32_e32 v66, 16, v60
	v_and_b32_e32 v67, 0xffff0000, v60
	v_pk_mul_f32 v[66:67], v[194:195], v[66:67]
	s_waitcnt lgkmcnt(1)
	v_lshlrev_b32_e32 v96, 16, v64
	v_cvt_pk_bf16_f32 v60, v66, v67
	v_lshlrev_b32_e32 v66, 16, v61
	v_and_b32_e32 v67, 0xffff0000, v61
	v_pk_mul_f32 v[66:67], v[196:197], v[66:67]
	v_and_b32_e32 v97, 0xffff0000, v64
	v_cvt_pk_bf16_f32 v61, v66, v67
	v_lshlrev_b32_e32 v66, 16, v62
	v_and_b32_e32 v67, 0xffff0000, v62
	v_pk_mul_f32 v[66:67], v[198:199], v[66:67]
	v_lshlrev_b32_e32 v64, 16, v65
	v_cvt_pk_bf16_f32 v62, v66, v67
	v_lshlrev_b32_e32 v66, 16, v63
	v_and_b32_e32 v67, 0xffff0000, v63
	v_pk_mul_f32 v[66:67], v[200:201], v[66:67]
	v_and_b32_e32 v65, 0xffff0000, v65
	v_cvt_pk_bf16_f32 v63, v66, v67
	ds_read_b64_tr_b16 v[202:203], v159 offset:34816
	ds_read_b64_tr_b16 v[204:205], v159 offset:35904
	ds_read_b128 v[206:209], v153
	ds_read_b128 v[210:213], v153 offset:16
	ds_read_b64_tr_b16 v[98:99], v160 offset:320
	ds_read_b64_tr_b16 v[66:67], v158 offset:352
	v_pk_mul_f32 v[52:53], v[194:195], v[96:97]
	ds_read_b64_tr_b16 v[96:97], v160
	ds_read_b64_tr_b16 v[100:101], v160 offset:32
	v_pk_mul_f32 v[54:55], v[196:197], v[64:65]
	v_cvt_pk_bf16_f32 v52, v52, v53
	v_cvt_pk_bf16_f32 v53, v54, v55
	s_waitcnt lgkmcnt(2)
	v_lshlrev_b32_e32 v54, 16, v66
	v_and_b32_e32 v55, 0xffff0000, v66
	v_pk_mul_f32 v[54:55], v[198:199], v[54:55]
	v_lshlrev_b32_e32 v56, 16, v67
	v_and_b32_e32 v57, 0xffff0000, v67
	v_pk_mul_f32 v[56:57], v[200:201], v[56:57]
	v_cvt_pk_bf16_f32 v54, v54, v55
	v_cvt_pk_bf16_f32 v55, v56, v57
	v_mfma_f32_16x16x32_bf16 v[60:63], v[48:51], v[60:63], 0
	s_nop 0
	v_mfma_f32_16x16x32_bf16 v[48:51], v[48:51], v[52:55], 0
	s_waitcnt lgkmcnt(1)
	v_lshlrev_b32_e32 v102, 16, v96
	v_and_b32_e32 v103, 0xffff0000, v96
	v_pk_mul_f32 v[102:103], v[206:207], v[102:103]
	s_nop 0
	v_cvt_pk_bf16_f32 v96, v102, v103
	v_lshlrev_b32_e32 v102, 16, v97
	v_and_b32_e32 v103, 0xffff0000, v97
	v_pk_mul_f32 v[102:103], v[208:209], v[102:103]
	s_nop 0
	v_cvt_pk_bf16_f32 v97, v102, v103
	v_lshlrev_b32_e32 v102, 16, v98
	v_and_b32_e32 v103, 0xffff0000, v98
	v_pk_mul_f32 v[102:103], v[210:211], v[102:103]
	s_nop 0
	v_cvt_pk_bf16_f32 v98, v102, v103
	v_lshlrev_b32_e32 v102, 16, v99
	v_and_b32_e32 v103, 0xffff0000, v99
	v_pk_mul_f32 v[102:103], v[212:213], v[102:103]
	s_nop 0
	v_cvt_pk_bf16_f32 v99, v102, v103
	s_nop 1
	v_mfma_f32_16x16x32_bf16 v[60:63], v[202:205], v[96:99], v[60:63]
	ds_read_b64_tr_b16 v[214:215], v161 offset:34816
	ds_read_b64_tr_b16 v[216:217], v161 offset:35904
	ds_read_b128 v[218:221], v154
	ds_read_b128 v[222:225], v154 offset:16
	ds_read_b64_tr_b16 v[96:97], v160 offset:352
	s_waitcnt lgkmcnt(5)
	v_lshlrev_b32_e32 v98, 16, v100
	v_and_b32_e32 v99, 0xffff0000, v100
	v_pk_mul_f32 v[56:57], v[206:207], v[98:99]
	v_lshlrev_b32_e32 v98, 16, v101
	v_and_b32_e32 v99, 0xffff0000, v101
	v_pk_mul_f32 v[58:59], v[208:209], v[98:99]
	ds_read_b64_tr_b16 v[98:99], v162 offset:320
	v_cvt_pk_bf16_f32 v56, v56, v57
	v_cvt_pk_bf16_f32 v57, v58, v59
	s_waitcnt lgkmcnt(1)
	v_lshlrev_b32_e32 v58, 16, v96
	v_and_b32_e32 v59, 0xffff0000, v96
	v_pk_mul_f32 v[58:59], v[210:211], v[58:59]
	v_lshlrev_b32_e32 v64, 16, v97
	v_and_b32_e32 v65, 0xffff0000, v97
	ds_read_b64_tr_b16 v[96:97], v162
	ds_read_b64_tr_b16 v[100:101], v162 offset:32
	v_pk_mul_f32 v[64:65], v[212:213], v[64:65]
	v_cvt_pk_bf16_f32 v58, v58, v59
	v_cvt_pk_bf16_f32 v59, v64, v65
	s_nop 1
	v_mfma_f32_16x16x32_bf16 v[48:51], v[202:205], v[56:59], v[48:51]
	s_waitcnt lgkmcnt(1)
	v_lshlrev_b32_e32 v102, 16, v96
	v_and_b32_e32 v103, 0xffff0000, v96
	v_pk_mul_f32 v[102:103], v[218:219], v[102:103]
	s_nop 0
	v_cvt_pk_bf16_f32 v96, v102, v103
	v_lshlrev_b32_e32 v102, 16, v97
	v_and_b32_e32 v103, 0xffff0000, v97
	v_pk_mul_f32 v[102:103], v[220:221], v[102:103]
	s_nop 0
	v_cvt_pk_bf16_f32 v97, v102, v103
	v_lshlrev_b32_e32 v102, 16, v98
	v_and_b32_e32 v103, 0xffff0000, v98
	v_pk_mul_f32 v[102:103], v[222:223], v[102:103]
	s_nop 0
	v_cvt_pk_bf16_f32 v98, v102, v103
	v_lshlrev_b32_e32 v102, 16, v99
	v_and_b32_e32 v103, 0xffff0000, v99
	v_pk_mul_f32 v[102:103], v[224:225], v[102:103]
	s_nop 0
	v_cvt_pk_bf16_f32 v99, v102, v103
	s_nop 1
	v_mfma_f32_16x16x32_bf16 v[60:63], v[214:217], v[96:99], v[60:63]
	ds_read_b64_tr_b16 v[96:97], v162 offset:352
	s_waitcnt lgkmcnt(1)
	v_lshlrev_b32_e32 v98, 16, v100
	v_and_b32_e32 v99, 0xffff0000, v100
	v_pk_mul_f32 v[56:57], v[218:219], v[98:99]
	v_lshlrev_b32_e32 v98, 16, v101
	v_and_b32_e32 v99, 0xffff0000, v101
	v_pk_mul_f32 v[58:59], v[220:221], v[98:99]
	v_cvt_pk_bf16_f32 v56, v56, v57
	v_cvt_pk_bf16_f32 v57, v58, v59
	s_waitcnt lgkmcnt(0)
	v_lshlrev_b32_e32 v58, 16, v96
	v_and_b32_e32 v59, 0xffff0000, v96
	v_pk_mul_f32 v[58:59], v[222:223], v[58:59]
	v_lshlrev_b32_e32 v64, 16, v97
	v_and_b32_e32 v65, 0xffff0000, v97
	v_pk_mul_f32 v[64:65], v[224:225], v[64:65]
	v_cvt_pk_bf16_f32 v58, v58, v59
	v_cvt_pk_bf16_f32 v59, v64, v65
	s_nop 1
	v_mfma_f32_16x16x32_bf16 v[48:51], v[214:217], v[56:59], v[48:51]
	ds_read_b64_tr_b16 v[52:53], v163 offset:34816
	ds_read_b64_tr_b16 v[54:55], v163 offset:35904
	ds_read_b128 v[226:229], v155
	ds_read_b128 v[64:67], v155 offset:16
	ds_read_b64_tr_b16 v[98:99], v164 offset:320
	ds_read_b64_tr_b16 v[96:97], v164
	ds_read_b64_tr_b16 v[100:101], v164 offset:32
	v_mov_b32_e32 v1, v234
	s_mov_b64 s[14:15], 0x4000
	v_lshl_add_u64 v[80:81], v[80:81], 0, s[14:15]
	s_waitcnt lgkmcnt(1)
	v_lshlrev_b32_e32 v102, 16, v96
	v_and_b32_e32 v103, 0xffff0000, v96
	v_pk_mul_f32 v[102:103], v[226:227], v[102:103]
	s_mov_b64 s[14:15], 0x1b0000
	v_cvt_pk_bf16_f32 v96, v102, v103
	v_lshlrev_b32_e32 v102, 16, v97
	v_and_b32_e32 v103, 0xffff0000, v97
	v_pk_mul_f32 v[102:103], v[228:229], v[102:103]
	s_add_i32 s1, s1, -1
	v_cvt_pk_bf16_f32 v97, v102, v103
	v_lshlrev_b32_e32 v102, 16, v98
	v_and_b32_e32 v103, 0xffff0000, v98
	v_pk_mul_f32 v[102:103], v[64:65], v[102:103]
	ds_read_b32 v1, v1
	v_cvt_pk_bf16_f32 v98, v102, v103
	v_lshlrev_b32_e32 v102, 16, v99
	v_and_b32_e32 v103, 0xffff0000, v99
	v_pk_mul_f32 v[102:103], v[66:67], v[102:103]
	s_waitcnt lgkmcnt(0)
	v_mul_f32_e32 v1, 0x3fb8aa3b, v1
	v_cvt_pk_bf16_f32 v99, v102, v103
	v_lshl_add_u64 v[82:83], v[82:83], 0, s[14:15]
	s_mov_b64 s[14:15], 0x200
	v_mfma_f32_16x16x32_bf16 v[60:63], v[52:55], v[96:99], v[60:63]
	ds_read_b64_tr_b16 v[96:97], v164 offset:352
	v_lshlrev_b32_e32 v98, 16, v100
	v_and_b32_e32 v99, 0xffff0000, v100
	v_pk_mul_f32 v[56:57], v[226:227], v[98:99]
	v_lshlrev_b32_e32 v98, 16, v101
	v_and_b32_e32 v99, 0xffff0000, v101
	v_pk_mul_f32 v[58:59], v[228:229], v[98:99]
	v_cvt_pk_bf16_f32 v56, v56, v57
	v_cvt_pk_bf16_f32 v57, v58, v59
	s_waitcnt lgkmcnt(0)
	v_lshlrev_b32_e32 v58, 16, v96
	v_and_b32_e32 v59, 0xffff0000, v96
	v_pk_mul_f32 v[58:59], v[64:65], v[58:59]
	v_lshlrev_b32_e32 v64, 16, v97
	v_and_b32_e32 v65, 0xffff0000, v97
	v_pk_mul_f32 v[64:65], v[66:67], v[64:65]
	v_cvt_pk_bf16_f32 v58, v58, v59
	v_cvt_pk_bf16_f32 v59, v64, v65
	s_barrier
	s_nop 0
	v_mfma_f32_16x16x32_bf16 v[48:51], v[52:55], v[56:59], v[48:51]
	v_exp_f32_e32 v52, v1
	v_lshl_add_u64 v[84:85], v[84:85], 0, s[70:71]
	v_lshl_add_u64 v[86:87], v[86:87], 0, s[70:71]
	v_pk_fma_f32 v[10:11], v[10:11], v[52:53], v[62:63] op_sel_hi:[1,0,1]
	v_pk_fma_f32 v[8:9], v[8:9], v[52:53], v[60:61] op_sel_hi:[1,0,1]
	s_nop 2
	v_pk_fma_f32 v[46:47], v[46:47], v[52:53], v[50:51] op_sel_hi:[1,0,1]
	v_pk_fma_f32 v[44:45], v[44:45], v[52:53], v[48:49] op_sel_hi:[1,0,1]
	v_cvt_pk_bf16_f32 v48, v8, v9
	v_cvt_pk_bf16_f32 v49, v10, v11
	ds_write_b64 v165, v[48:49]
	v_cvt_pk_bf16_f32 v48, v44, v45
	v_cvt_pk_bf16_f32 v49, v46, v47
	v_lshl_add_u64 v[88:89], v[88:89], 0, s[14:15]
	v_lshl_add_u64 v[90:91], v[90:91], 0, s[70:71]
	s_cmp_lg_u32 s1, -1
	s_waitcnt vmcnt(2)
	v_mov_b64_e32 v[96:97], v[94:95]
	v_mov_b64_e32 v[98:99], v[92:93]
	ds_write_b64 v165, v[48:49] offset:4352
	v_add_u32_e32 v129, 0x600, v129
	v_add_u32_e32 v131, 0x600, v131
	v_add_u32_e32 v132, 0x600, v132
	v_add_u32_e32 v133, 0x600, v133
	v_add_u32_e32 v134, 0x600, v134
	v_add_u32_e32 v135, 0x600, v135
	v_add_u32_e32 v136, 0x600, v136
	v_add_u32_e32 v137, 0x600, v137
	v_add_u32_e32 v138, 0x600, v138
	v_add_u32_e32 v139, 0x600, v139
	v_add_u32_e32 v140, 0x600, v140
	v_add_u32_e32 v141, 0x600, v141
	v_add_u32_e32 v142, 0x600, v142
	v_add_u32_e32 v143, 0x600, v143
	v_add_u32_e32 v144, 0x600, v144
	v_add_u32_e32 v148, 0x600, v148
	v_add_u32_e32 v149, 0x600, v149
	v_add_u32_e32 v152, 0x600, v152
	v_add_u32_e32 v153, 0x600, v153
	v_add_u32_e32 v154, 0x600, v154
	v_add_u32_e32 v155, 0x600, v155
	v_add_u32_e32 v234, 0x600, v234
	s_cbranch_scc0 .LBB0_458
.LBB0_466:
	v_cndmask_b32_e64 v0, 0, 1, s[34:35]
	v_cmp_ne_u32_e64 s[14:15], 1, v0
	s_andn2_b64 vcc, exec, s[34:35]
	s_branch .LBB0_475
.LBB0_475:
	s_cmp_eq_u32 s1, 0
	s_waitcnt vmcnt(10)
	ds_write_b128 v121, v[4:7]
	s_waitcnt vmcnt(8)
	ds_write_b128 v150, v[16:19] offset:34816
	ds_write_b128 v150, v[12:15]
	s_waitcnt vmcnt(6)
	ds_write_b128 v150, v[24:27] offset:43520
	ds_write_b128 v150, v[20:23] offset:8704
	s_waitcnt vmcnt(3)
	ds_write_b128 v150, v[32:35] offset:52224
	ds_write_b128 v150, v[28:31] offset:17408
	ds_write_b128 v150, v[36:39] offset:60928
	s_waitcnt vmcnt(2)
	ds_write_b128 v150, v[40:43] offset:26112
	s_waitcnt lgkmcnt(0)
	s_barrier
	s_cbranch_scc1 .LBB0_479
	v_lshl_add_u64 v[28:29], s[92:93], 0, v[84:85]
	v_add_co_u32_e32 v12, vcc, 0xedc1000, v28
	v_lshl_add_u64 v[0:1], s[92:93], 0, v[86:87]
	s_nop 0
	v_addc_co_u32_e32 v13, vcc, 0, v29, vcc
	global_load_dwordx4 v[4:7], v[0:1], off
	global_load_dwordx4 v[16:19], v[12:13], off
	v_add_co_u32_e32 v0, vcc, 0xedf1000, v28
	s_nop 1
	v_addc_co_u32_e32 v1, vcc, 0, v29, vcc
	v_add_co_u32_e32 v30, vcc, 0xee21000, v28
	global_load_dwordx4 v[12:15], v[12:13], off offset:1024
	s_nop 0
	global_load_dwordx4 v[24:27], v[0:1], off
	v_addc_co_u32_e32 v31, vcc, 0, v29, vcc
	global_load_dwordx4 v[20:23], v[0:1], off offset:1024
	global_load_dwordx4 v[32:35], v[30:31], off
	v_add_co_u32_e32 v0, vcc, 0xee51000, v28
	s_nop 1
	v_addc_co_u32_e32 v1, vcc, 0, v29, vcc
	global_load_dwordx4 v[28:31], v[30:31], off offset:1024
	s_nop 0
	global_load_dwordx4 v[36:39], v[0:1], off
	global_load_dwordx4 v[40:43], v[0:1], off offset:1024
	s_and_b64 vcc, exec, s[14:15]
	s_branch .LBB0_478

.LBB0_508:
	ds_read_b128 v[194:197], v156
	ds_read_b128 v[198:201], v156 offset:4352
	ds_read_b128 v[202:205], v78 offset:64
	ds_read_b128 v[206:209], v156 offset:64
	ds_read_b128 v[210:213], v156 offset:4416
	ds_read_b128 v[214:217], v78 offset:128
	ds_read_b128 v[218:221], v156 offset:128
	ds_read_b128 v[222:225], v156 offset:4480
	ds_read_b128 v[226:229], v78 offset:192
	ds_read_b128 v[230:233], v156 offset:192
	ds_read_b128 v[56:59], v78
	s_waitcnt vmcnt(12)
	v_lshlrev_b32_e32 v1, 16, v98
	v_mul_f32_e32 v0, 0x3fb8aa3b, v75
	v_and_b32_e32 v3, 0xffff0000, v98
	s_waitcnt lgkmcnt(0)
	v_mfma_f32_16x16x32_bf16 v[60:63], v[194:197], v[56:59], 0
	ds_read_b128 v[194:197], v156 offset:4544
	v_exp_f32_e32 v0, v0
	v_mfma_f32_16x16x32_bf16 v[56:59], v[198:201], v[56:59], 0
	v_mfma_f32_16x16x32_bf16 v[60:63], v[206:209], v[202:205], v[60:63]
	v_mfma_f32_16x16x32_bf16 v[56:59], v[210:213], v[202:205], v[56:59]
	v_mfma_f32_16x16x32_bf16 v[60:63], v[218:221], v[214:217], v[60:63]
	v_mfma_f32_16x16x32_bf16 v[56:59], v[222:225], v[214:217], v[56:59]
	v_mfma_f32_16x16x32_bf16 v[100:103], v[230:233], v[226:229], v[60:63]
	s_nop 2
	s_waitcnt lgkmcnt(0)
	v_mfma_f32_16x16x32_bf16 v[56:59], v[194:197], v[226:229], v[56:59]
	s_nop 0
	ds_read2_b64 v[60:63], v151 offset1:4
	s_nop 0
	v_pk_fma_f32 v[48:49], v[0:1], v[100:101], v[48:49] op_sel_hi:[0,1,1]
	s_waitcnt lgkmcnt(0)
	v_lshlrev_b32_e32 v64, 16, v60
	v_and_b32_e32 v65, 0xffff0000, v60
	v_mul_f32_e32 v60, 0xbfb8aa3b, v1
	v_exp_f32_e32 v66, v60
	v_mul_f32_e32 v60, 0xbfb8aa3b, v3
	v_exp_f32_e32 v67, v60
	v_pk_fma_f32 v[48:49], v[68:69], v[64:65], v[48:49]
	v_pk_add_f32 v[64:65], v[66:67], 1.0 op_sel_hi:[1,0]
	s_nop 0
	v_div_scale_f32 v60, s[14:15], v65, v65, v3
	v_rcp_f32_e32 v66, v60
	s_nop 0
	v_fma_f32 v67, -v60, v66, 1.0
	v_fmac_f32_e32 v66, v67, v66
	v_div_scale_f32 v67, vcc, v3, v65, v3
	v_mul_f32_e32 v75, v67, v66
	v_fma_f32 v98, -v60, v75, v67
	v_fmac_f32_e32 v75, v98, v66
	v_fma_f32 v60, -v60, v75, v67
	v_div_fmas_f32 v60, v60, v66, v75
	v_div_fixup_f32 v65, v60, v65, v3
	v_div_scale_f32 v3, s[14:15], v64, v64, v1
	v_rcp_f32_e32 v60, v3
	s_nop 0
	v_fma_f32 v66, -v3, v60, 1.0
	v_fmac_f32_e32 v60, v66, v60
	v_div_scale_f32 v66, vcc, v1, v64, v1
	v_mul_f32_e32 v67, v66, v60
	v_fma_f32 v75, -v3, v67, v66
	v_fmac_f32_e32 v67, v75, v60
	v_fma_f32 v3, -v3, v67, v66
	v_div_fmas_f32 v3, v3, v60, v67
	v_div_fixup_f32 v64, v3, v64, v1
	v_lshlrev_b32_e32 v1, 16, v99
	v_and_b32_e32 v3, 0xffff0000, v99
	v_lshlrev_b32_e32 v60, 16, v61
	v_and_b32_e32 v61, 0xffff0000, v61
	v_pk_fma_f32 v[50:51], v[0:1], v[102:103], v[50:51] op_sel_hi:[0,1,1]
	v_mul_f32_e32 v66, 0xbfb8aa3b, v1
	v_pk_fma_f32 v[50:51], v[68:69], v[60:61], v[50:51]
	v_mul_f32_e32 v60, 0xbfb8aa3b, v3
	v_exp_f32_e32 v66, v66
	v_exp_f32_e32 v67, v60
	v_pk_mul_f32 v[64:65], v[64:65], v[48:49]
	v_pk_add_f32 v[60:61], v[66:67], 1.0 op_sel_hi:[1,0]
	s_nop 0
	v_div_scale_f32 v66, s[14:15], v61, v61, v3
	v_rcp_f32_e32 v67, v66
	v_pk_mul_f32 v[48:49], v[64:65], v[64:65]
	v_cvt_pk_bf16_f32 v64, v64, v65
	v_fma_f32 v75, -v66, v67, 1.0
	v_fmac_f32_e32 v67, v75, v67
	v_div_scale_f32 v75, vcc, v3, v61, v3
	v_mul_f32_e32 v98, v75, v67
	v_fma_f32 v99, -v66, v98, v75
	v_fmac_f32_e32 v98, v99, v67
	v_fma_f32 v66, -v66, v98, v75
	v_div_fmas_f32 v66, v66, v67, v98
	v_div_fixup_f32 v61, v66, v61, v3
	v_div_scale_f32 v3, s[14:15], v60, v60, v1
	v_rcp_f32_e32 v66, v3
	s_mov_b32 s14, 0x1b800000
	v_fma_f32 v67, -v3, v66, 1.0
	v_fmac_f32_e32 v66, v67, v66
	v_div_scale_f32 v67, vcc, v1, v60, v1
	v_mul_f32_e32 v75, v67, v66
	v_fma_f32 v98, -v3, v75, v67
	v_fmac_f32_e32 v75, v98, v66
	v_fma_f32 v3, -v3, v75, v67
	v_div_fmas_f32 v3, v3, v66, v75
	v_div_fixup_f32 v60, v3, v60, v1
	v_pk_mul_f32 v[50:51], v[60:61], v[50:51]
	s_waitcnt vmcnt(11)
	v_lshlrev_b32_e32 v1, 16, v96
	v_pk_mul_f32 v[60:61], v[50:51], v[50:51]
	v_cvt_pk_bf16_f32 v65, v50, v51
	v_lshl_add_u64 v[50:51], s[92:93], 0, v[90:91]
	v_add_co_u32_e32 v50, vcc, s14, v50
	v_and_b32_e32 v3, 0xffff0000, v96
	s_nop 0
	v_addc_co_u32_e32 v51, vcc, 0, v51, vcc
	global_store_dwordx2 v[50:51], v[64:65], off
	v_lshlrev_b32_e32 v64, 16, v62
	v_and_b32_e32 v65, 0xffff0000, v62
	v_mul_f32_e32 v62, 0xbfb8aa3b, v1
	v_pk_fma_f32 v[52:53], v[0:1], v[56:57], v[52:53] op_sel_hi:[0,1,1]
	v_mul_f32_e32 v56, 0xbfb8aa3b, v3
	v_exp_f32_e32 v66, v62
	v_exp_f32_e32 v67, v56
	v_pk_fma_f32 v[52:53], v[68:69], v[64:65], v[52:53]
	v_pk_add_f32 v[56:57], v[66:67], 1.0 op_sel_hi:[1,0]
	s_nop 0
	v_div_scale_f32 v62, s[14:15], v57, v57, v3
	v_rcp_f32_e32 v64, v62
	s_nop 0
	v_fma_f32 v65, -v62, v64, 1.0
	v_fmac_f32_e32 v64, v65, v64
	v_div_scale_f32 v65, vcc, v3, v57, v3
	v_mul_f32_e32 v66, v65, v64
	v_fma_f32 v67, -v62, v66, v65
	v_fmac_f32_e32 v66, v67, v64
	v_fma_f32 v62, -v62, v66, v65
	v_div_fmas_f32 v62, v62, v64, v66
	v_div_fixup_f32 v57, v62, v57, v3
	v_div_scale_f32 v3, s[14:15], v56, v56, v1
	v_rcp_f32_e32 v62, v3
	s_nop 0
	v_fma_f32 v64, -v3, v62, 1.0
	v_fmac_f32_e32 v62, v64, v62
	v_div_scale_f32 v64, vcc, v1, v56, v1
	v_mul_f32_e32 v65, v64, v62
	v_fma_f32 v66, -v3, v65, v64
	v_fmac_f32_e32 v65, v66, v62
	v_fma_f32 v3, -v3, v65, v64
	v_div_fmas_f32 v3, v3, v62, v65
	v_div_fixup_f32 v56, v3, v56, v1
	v_lshlrev_b32_e32 v3, 16, v97
	v_and_b32_e32 v66, 0xffff0000, v97
	v_mul_f32_e32 v1, 0xbfb8aa3b, v3
	v_exp_f32_e32 v64, v1
	v_pk_fma_f32 v[0:1], v[0:1], v[58:59], v[54:55] op_sel_hi:[0,1,1]
	v_mul_f32_e32 v54, 0xbfb8aa3b, v66
	v_exp_f32_e32 v65, v54
	v_lshlrev_b32_e32 v62, 16, v63
	v_and_b32_e32 v63, 0xffff0000, v63
	v_pk_fma_f32 v[0:1], v[68:69], v[62:63], v[0:1]
	v_pk_add_f32 v[54:55], v[64:65], 1.0 op_sel_hi:[1,0]
	v_pk_mul_f32 v[52:53], v[56:57], v[52:53]
	v_div_scale_f32 v58, s[14:15], v55, v55, v66
	v_rcp_f32_e32 v59, v58
	v_pk_mul_f32 v[56:57], v[52:53], v[52:53]
	v_fma_f32 v62, -v58, v59, 1.0
	v_fmac_f32_e32 v59, v62, v59
	v_div_scale_f32 v62, vcc, v66, v55, v66
	v_mul_f32_e32 v63, v62, v59
	v_fma_f32 v64, -v58, v63, v62
	v_fmac_f32_e32 v63, v64, v59
	v_fma_f32 v58, -v58, v63, v62
	v_div_fmas_f32 v58, v58, v59, v63
	v_div_fixup_f32 v55, v58, v55, v66
	v_div_scale_f32 v58, s[14:15], v54, v54, v3
	v_rcp_f32_e32 v59, v58
	s_nop 0
	v_fma_f32 v62, -v58, v59, 1.0
	v_fmac_f32_e32 v59, v62, v59
	v_div_scale_f32 v62, vcc, v3, v54, v3
	v_mul_f32_e32 v63, v62, v59
	v_fma_f32 v64, -v58, v63, v62
	v_fmac_f32_e32 v63, v64, v59
	v_fma_f32 v58, -v58, v63, v62
	v_div_fmas_f32 v58, v58, v59, v63
	v_div_fixup_f32 v54, v58, v54, v3
	v_add_f32_e32 v3, v48, v49
	v_pk_mul_f32 v[0:1], v[54:55], v[0:1]
	v_add_f32_e32 v3, v60, v3
	v_pk_mul_f32 v[54:55], v[0:1], v[0:1]
	v_add_f32_e32 v3, v61, v3
	v_cvt_pk_bf16_f32 v49, v0, v1
	v_and_b32_e32 v0, 64, v73
	v_add_f32_e32 v3, v56, v3
	v_xor_b32_e32 v1, 16, v73
	v_add_u32_e32 v0, 64, v0
	v_add_f32_e32 v3, v57, v3
	v_cmp_lt_i32_e32 vcc, v1, v0
	v_add_f32_e32 v3, v54, v3
	v_add_f32_e32 v54, v55, v3
	v_cndmask_b32_e32 v1, v73, v1, vcc
	v_lshlrev_b32_e32 v3, 2, v1
	ds_bpermute_b32 v1, v3, v54
	v_cvt_pk_bf16_f32 v48, v52, v53
	global_store_dwordx2 v[50:51], v[48:49], off offset:32
	v_xor_b32_e32 v48, 32, v73
	v_cmp_lt_i32_e32 vcc, v48, v0
	s_waitcnt lgkmcnt(0)
	v_add_f32_e32 v1, v54, v1
	v_cndmask_b32_e32 v48, v73, v48, vcc
	v_lshlrev_b32_e32 v75, 2, v48
	ds_bpermute_b32 v48, v75, v1
	s_and_saveexec_b64 s[14:15], s[2:3]
	s_cbranch_execz .LBB0_465
	v_lshl_add_u64 v[50:51], s[92:93], 0, v[88:89]
	s_waitcnt lgkmcnt(0)
	v_add_f32_e32 v1, v1, v48
	global_atomic_add_f32 v[50:51], v1, off
	s_branch .LBB0_465
